# in-proj epilogue: the 8 row sum-of-squares loads hoisted to the epilogue head with counted vmcnt waits
# speedup vs baseline: 1.0137x; 1.0137x over previous
;     __device__ __forceinline__ void operator()(const f32x4 (&acc)[2][2][4][2], const Unit& u, int wr, int wc, int fr, int fq) const {
;         const int pn = u.pn;
;         const int mode = (pn < 4) ? 1 : ((pn == 6 || pn == 7 || pn >= 14) ? 2 : 0);
;         const float sc = (pn < 2 || pn == 8 || pn == 9) ? C2 : 1.f;
;         const int colb = pn * 256 + wc * 32 + 8 * fq;
;         float mxb[2] = {0.f, 0.f};
; #pragma unroll
;         for (int ai = 0; ai < 2; ++ai)
; #pragma unroll
;             for (int m = 0; m < 4; ++m) {
;                 const int row = u.pm * BM + ai * HALF + wr * 64 + m * 16 + fr;
;                 const float rs = rsqrtf(sumsq[row] * (1.0f / DM) + NORM_EPS) * sc;
;                 const int bb = row >> 13, tt = row & 8191; const size_t R = (size_t)bb * LP + 64 + tt; const int pos = 16 + tt;
; #pragma unroll
;                 for (int bj = 0; bj < 2; ++bj) {
;                     const int col = colb + bj * HALF;
;                     f32x4 v0 = acc[ai][bj][m][0] * rs, v1 = acc[ai][bj][m][1] * rs;
;                     if (mode == 1) {
;                         const int j0 = (col & 63) >> 1;
;                         const f32x4* cs = (const f32x4*)(rope + ((size_t)pos * 32 + j0) * 2);
;                         const f32x4 a = cs[0], b = cs[1];
;                         f32x4 w0, w1;
;                         w0[0] = v0[0] * a[0] - v0[1] * a[1]; w0[1] = v0[1] * a[0] + v0[0] * a[1];
;                         w0[2] = v0[2] * a[2] - v0[3] * a[3]; w0[3] = v0[3] * a[2] + v0[2] * a[3];
;                         w1[0] = v1[0] * b[0] - v1[1] * b[1]; w1[1] = v1[1] * b[0] + v1[0] * b[1];
;                         w1[2] = v1[2] * b[2] - v1[3] * b[3]; w1[3] = v1[3] * b[2] + v1[2] * b[3];
;                         v0 = w0; v1 = w1;
;                     } else if (mode == 2) {
; #pragma unroll
;                         for (int i = 0; i < 4; ++i) { v0[i] = v0[i] * __builtin_amdgcn_rcpf(1.f + __builtin_amdgcn_exp2f(-v0[i] * LOG2E)); v1[i] = v1[i] * __builtin_amdgcn_rcpf(1.f + __builtin_amdgcn_exp2f(-v1[i] * LOG2E)); }
.LBB0_240:
	s_and_b32 s0, s88, 0x7ffffffe
	s_cmp_eq_u32 s0, 6
	s_cselect_b64 s[0:1], -1, 0
	s_cmp_gt_i32 s88, 13
	s_cselect_b64 s[16:17], -1, 0
	s_or_b64 s[0:1], s[16:17], s[0:1]
	s_and_b64 s[0:1], s[0:1], exec
	s_cselect_b32 s0, 2, 0
	s_cmp_gt_i32 s88, 3
	s_cselect_b32 s61, s0, 1
	s_cmp_lt_i32 s88, 2
	s_cselect_b64 s[0:1], -1, 0
	s_and_b32 s16, s88, -2
	s_cmp_eq_u32 s16, 8
	s_cselect_b64 s[16:17], -1, 0
	s_lshl_b32 s63, s46, 8
	s_add_i32 s63, s63, s34
	v_or_b32_e32 v144, s63, v115
	v_ashrrev_i32_e32 v145, 31, v144
	v_lshl_add_u64 v[146:147], v[144:145], 2, s[54:55]
	global_load_dword v224, v[146:147], off
	global_load_dword v225, v[146:147], off offset:64
	global_load_dword v226, v[146:147], off offset:128
	global_load_dword v227, v[146:147], off offset:192
	global_load_dword v228, v[146:147], off offset:512
	global_load_dword v229, v[146:147], off offset:576
	global_load_dword v230, v[146:147], off offset:640
	global_load_dword v231, v[146:147], off offset:704
	s_or_b64 vcc, s[0:1], s[16:17]
	v_cndmask_b32_e32 v162, 1.0, v219, vcc
	s_mov_b64 s[0:1], -1
	s_cmp_gt_i32 s61, 1
	s_waitcnt vmcnt(7)
	v_fmamk_f32 v0, v224, 0x3a800000, v202
	v_cmp_gt_f32_e32 vcc, s18, v0
	v_mul_f32_e32 v145, 0x4b800000, v0
	s_nop 0
	v_cndmask_b32_e32 v0, v0, v145, vcc
	v_rsq_f32_e32 v0, v0
	s_nop 0
	v_mul_f32_e32 v145, 0x45800000, v0
	v_cndmask_b32_e32 v0, v0, v145, vcc
	v_mul_f32_e32 v148, v162, v0
	v_pk_mul_f32 v[130:131], v[130:131], v[148:149] op_sel_hi:[1,0]
	v_pk_mul_f32 v[128:129], v[128:129], v[148:149] op_sel_hi:[1,0]
	v_pk_mul_f32 v[126:127], v[126:127], v[148:149] op_sel_hi:[1,0]
	v_pk_mul_f32 v[124:125], v[124:125], v[148:149] op_sel_hi:[1,0]
	s_cbranch_scc0 .LBB0_242
	v_mul_f32_e32 v0, 0xbfb8aa3b, v128
	v_exp_f32_e32 v0, v0
	v_mul_f32_e32 v145, 0xbfb8aa3b, v124
	v_mul_f32_e32 v149, 0xbfb8aa3b, v129
	v_exp_f32_e32 v145, v145
	v_exp_f32_e32 v149, v149
	v_add_f32_e32 v0, 1.0, v0
	v_rcp_f32_e32 v150, v0
	v_add_f32_e32 v0, 1.0, v145
	v_mul_f32_e32 v145, 0xbfb8aa3b, v130
	v_rcp_f32_e32 v164, v0
	v_add_f32_e32 v0, 1.0, v149
	v_exp_f32_e32 v145, v145
	v_mul_f32_e32 v149, 0xbfb8aa3b, v126
	v_exp_f32_e32 v149, v149
	v_rcp_f32_e32 v151, v0
	v_add_f32_e32 v145, 1.0, v145
	v_rcp_f32_e32 v152, v145
	v_add_f32_e32 v145, 1.0, v149
	v_mul_f32_e32 v149, 0xbfb8aa3b, v131
	v_mul_f32_e32 v0, 0xbfb8aa3b, v125
	v_exp_f32_e32 v149, v149
	v_mul_f32_e32 v153, 0xbfb8aa3b, v127
	v_exp_f32_e32 v0, v0
	v_exp_f32_e32 v154, v153
	v_rcp_f32_e32 v166, v145
	v_add_f32_e32 v145, 1.0, v149
	v_add_f32_e32 v0, 1.0, v0
	v_rcp_f32_e32 v153, v145
	v_add_f32_e32 v145, 1.0, v154
	v_rcp_f32_e32 v167, v145
	v_rcp_f32_e32 v165, v0
	v_pk_mul_f32 v[154:155], v[130:131], v[152:153]
	v_pk_mul_f32 v[156:157], v[128:129], v[150:151]
	v_pk_mul_f32 v[152:153], v[126:127], v[166:167]
	v_pk_mul_f32 v[150:151], v[124:125], v[164:165]
	s_mov_b64 s[0:1], 0

;     __device__ __forceinline__ void operator()(const f32x4 (&acc)[2][2][4][2], const Unit& u, int wr, int wc, int fr, int fq) const {
;     ...
;                 const int row = u.pm * BM + ai * HALF + wr * 64 + m * 16 + fr;
;                 const float rs = rsqrtf(sumsq[row] * (1.0f / DM) + NORM_EPS) * sc;
;                 const int bb = row >> 13, tt = row & 8191; const size_t R = (size_t)bb * LP + 64 + tt; const int pos = 16 + tt;
; #pragma unroll
;                 for (int bj = 0; bj < 2; ++bj) {
;                     const int col = colb + bj * HALF;
;                     f32x4 v0 = acc[ai][bj][m][0] * rs, v1 = acc[ai][bj][m][1] * rs;
;                     if (mode == 1) {
;                         const int j0 = (col & 63) >> 1;
;                         const f32x4* cs = (const f32x4*)(rope + ((size_t)pos * 32 + j0) * 2);
;                         const f32x4 a = cs[0], b = cs[1];
;                         f32x4 w0, w1;
;                         w0[0] = v0[0] * a[0] - v0[1] * a[1]; w0[1] = v0[1] * a[0] + v0[0] * a[1];
;                         w0[2] = v0[2] * a[2] - v0[3] * a[3]; w0[3] = v0[3] * a[2] + v0[2] * a[3];
;                         w1[0] = v1[0] * b[0] - v1[1] * b[1]; w1[1] = v1[1] * b[0] + v1[0] * b[1];
;                         w1[2] = v1[2] * b[2] - v1[3] * b[3]; w1[3] = v1[3] * b[2] + v1[2] * b[3];
;                         v0 = w0; v1 = w1;
;                     } else if (mode == 2) {
; #pragma unroll
;                         for (int i = 0; i < 4; ++i) { v0[i] = v0[i] * __builtin_amdgcn_rcpf(1.f + __builtin_amdgcn_exp2f(-v0[i] * LOG2E)); v1[i] = v1[i] * __builtin_amdgcn_rcpf(1.f + __builtin_amdgcn_exp2f(-v1[i] * LOG2E)); }
.LBB0_257:
	s_nop 0
	s_cmp_gt_i32 s61, 1
	s_mov_b64 s[0:1], -1
	s_waitcnt vmcnt(8)
	v_fmamk_f32 v0, v225, 0x3a800000, v202
	v_mul_f32_e32 v116, 0x4b800000, v0
	v_cmp_gt_f32_e32 vcc, s18, v0
	s_nop 1
	v_cndmask_b32_e32 v0, v0, v116, vcc
	v_rsq_f32_e32 v0, v0
	s_nop 0
	v_mul_f32_e32 v116, 0x45800000, v0
	v_cndmask_b32_e32 v0, v0, v116, vcc
	v_mul_f32_e32 v116, v162, v0
	v_pk_mul_f32 v[112:113], v[112:113], v[116:117] op_sel_hi:[1,0]
	v_pk_mul_f32 v[110:111], v[110:111], v[116:117] op_sel_hi:[1,0]
	v_pk_mul_f32 v[108:109], v[108:109], v[116:117] op_sel_hi:[1,0]
	v_pk_mul_f32 v[106:107], v[106:107], v[116:117] op_sel_hi:[1,0]
	s_cbranch_scc0 .LBB0_259
	v_mul_f32_e32 v0, 0xbfb8aa3b, v110
	v_exp_f32_e32 v0, v0
	v_mul_f32_e32 v117, 0xbfb8aa3b, v106
	v_exp_f32_e32 v117, v117
	v_mul_f32_e32 v118, 0xbfb8aa3b, v111
	v_add_f32_e32 v0, 1.0, v0
	v_exp_f32_e32 v119, v118
	v_rcp_f32_e32 v118, v0
	v_add_f32_e32 v0, 1.0, v117
	v_mul_f32_e32 v117, 0xbfb8aa3b, v112
	v_exp_f32_e32 v117, v117
	v_mul_f32_e32 v120, 0xbfb8aa3b, v108
	v_exp_f32_e32 v121, v120
	v_rcp_f32_e32 v130, v0
	v_add_f32_e32 v117, 1.0, v117
	v_add_f32_e32 v0, 1.0, v119
	v_rcp_f32_e32 v120, v117
	v_add_f32_e32 v117, 1.0, v121
	v_mul_f32_e32 v121, 0xbfb8aa3b, v113
	v_rcp_f32_e32 v119, v0
	v_mul_f32_e32 v0, 0xbfb8aa3b, v107
	v_exp_f32_e32 v121, v121
	v_mul_f32_e32 v122, 0xbfb8aa3b, v109
	v_exp_f32_e32 v0, v0
	v_exp_f32_e32 v122, v122
	v_rcp_f32_e32 v148, v117
	v_add_f32_e32 v117, 1.0, v121
	v_add_f32_e32 v0, 1.0, v0
	v_rcp_f32_e32 v121, v117
	v_add_f32_e32 v117, 1.0, v122
	v_rcp_f32_e32 v149, v117
	v_rcp_f32_e32 v131, v0
	v_pk_mul_f32 v[122:123], v[112:113], v[120:121]
	v_pk_mul_f32 v[128:129], v[110:111], v[118:119]
	v_pk_mul_f32 v[120:121], v[108:109], v[148:149]
	v_pk_mul_f32 v[118:119], v[106:107], v[130:131]
	s_mov_b64 s[0:1], 0

;     __device__ __forceinline__ void operator()(const f32x4 (&acc)[2][2][4][2], const Unit& u, int wr, int wc, int fr, int fq) const {
;     ...
;                 const int row = u.pm * BM + ai * HALF + wr * 64 + m * 16 + fr;
;                 const float rs = rsqrtf(sumsq[row] * (1.0f / DM) + NORM_EPS) * sc;
;                 const int bb = row >> 13, tt = row & 8191; const size_t R = (size_t)bb * LP + 64 + tt; const int pos = 16 + tt;
; #pragma unroll
;                 for (int bj = 0; bj < 2; ++bj) {
;                     const int col = colb + bj * HALF;
;                     f32x4 v0 = acc[ai][bj][m][0] * rs, v1 = acc[ai][bj][m][1] * rs;
;                     if (mode == 1) {
;                         const int j0 = (col & 63) >> 1;
;                         const f32x4* cs = (const f32x4*)(rope + ((size_t)pos * 32 + j0) * 2);
;                         const f32x4 a = cs[0], b = cs[1];
;                         f32x4 w0, w1;
;                         w0[0] = v0[0] * a[0] - v0[1] * a[1]; w0[1] = v0[1] * a[0] + v0[0] * a[1];
;                         w0[2] = v0[2] * a[2] - v0[3] * a[3]; w0[3] = v0[3] * a[2] + v0[2] * a[3];
;                         w1[0] = v1[0] * b[0] - v1[1] * b[1]; w1[1] = v1[1] * b[0] + v1[0] * b[1];
;                         w1[2] = v1[2] * b[2] - v1[3] * b[3]; w1[3] = v1[3] * b[2] + v1[2] * b[3];
;                         v0 = w0; v1 = w1;
;                     } else if (mode == 2) {
; #pragma unroll
;                         for (int i = 0; i < 4; ++i) { v0[i] = v0[i] * __builtin_amdgcn_rcpf(1.f + __builtin_amdgcn_exp2f(-v0[i] * LOG2E)); v1[i] = v1[i] * __builtin_amdgcn_rcpf(1.f + __builtin_amdgcn_exp2f(-v1[i] * LOG2E)); }
.LBB0_273:
	s_nop 0
	s_cmp_gt_i32 s61, 1
	s_mov_b64 s[0:1], -1
	s_waitcnt vmcnt(9)
	v_fmamk_f32 v0, v226, 0x3a800000, v202
	v_mul_f32_e32 v98, 0x4b800000, v0
	v_cmp_gt_f32_e32 vcc, s18, v0
	s_nop 1
	v_cndmask_b32_e32 v0, v0, v98, vcc
	v_rsq_f32_e32 v0, v0
	s_nop 0
	v_mul_f32_e32 v98, 0x45800000, v0
	v_cndmask_b32_e32 v0, v0, v98, vcc
	v_mul_f32_e32 v98, v162, v0
	v_pk_mul_f32 v[96:97], v[96:97], v[98:99] op_sel_hi:[1,0]
	v_pk_mul_f32 v[94:95], v[94:95], v[98:99] op_sel_hi:[1,0]
	v_pk_mul_f32 v[92:93], v[92:93], v[98:99] op_sel_hi:[1,0]
	v_pk_mul_f32 v[90:91], v[90:91], v[98:99] op_sel_hi:[1,0]
	s_cbranch_scc0 .LBB0_275
	v_mul_f32_e32 v0, 0xbfb8aa3b, v94
	v_exp_f32_e32 v0, v0
	v_mul_f32_e32 v99, 0xbfb8aa3b, v90
	v_exp_f32_e32 v99, v99
	v_mul_f32_e32 v100, 0xbfb8aa3b, v95
	v_add_f32_e32 v0, 1.0, v0
	v_exp_f32_e32 v101, v100
	v_rcp_f32_e32 v100, v0
	v_add_f32_e32 v0, 1.0, v99
	v_mul_f32_e32 v99, 0xbfb8aa3b, v96
	v_exp_f32_e32 v99, v99
	v_mul_f32_e32 v102, 0xbfb8aa3b, v92
	v_exp_f32_e32 v103, v102
	v_rcp_f32_e32 v108, v0
	v_add_f32_e32 v99, 1.0, v99
	v_add_f32_e32 v0, 1.0, v101
	v_rcp_f32_e32 v102, v99
	v_add_f32_e32 v99, 1.0, v103
	v_mul_f32_e32 v103, 0xbfb8aa3b, v97
	v_rcp_f32_e32 v101, v0
	v_mul_f32_e32 v0, 0xbfb8aa3b, v91
	v_exp_f32_e32 v103, v103
	v_mul_f32_e32 v104, 0xbfb8aa3b, v93
	v_exp_f32_e32 v0, v0
	v_exp_f32_e32 v104, v104
	v_rcp_f32_e32 v110, v99
	v_add_f32_e32 v99, 1.0, v103
	v_add_f32_e32 v0, 1.0, v0
	v_rcp_f32_e32 v103, v99
	v_add_f32_e32 v99, 1.0, v104
	v_rcp_f32_e32 v111, v99
	v_rcp_f32_e32 v109, v0
	v_pk_mul_f32 v[104:105], v[96:97], v[102:103]
	v_pk_mul_f32 v[106:107], v[94:95], v[100:101]
	v_pk_mul_f32 v[102:103], v[92:93], v[110:111]
	v_pk_mul_f32 v[100:101], v[90:91], v[108:109]
	s_mov_b64 s[0:1], 0

;     __device__ __forceinline__ void operator()(const f32x4 (&acc)[2][2][4][2], const Unit& u, int wr, int wc, int fr, int fq) const {
;     ...
;                 const int row = u.pm * BM + ai * HALF + wr * 64 + m * 16 + fr;
;                 const float rs = rsqrtf(sumsq[row] * (1.0f / DM) + NORM_EPS) * sc;
;                 const int bb = row >> 13, tt = row & 8191; const size_t R = (size_t)bb * LP + 64 + tt; const int pos = 16 + tt;
; #pragma unroll
;                 for (int bj = 0; bj < 2; ++bj) {
;                     const int col = colb + bj * HALF;
;                     f32x4 v0 = acc[ai][bj][m][0] * rs, v1 = acc[ai][bj][m][1] * rs;
;                     if (mode == 1) {
;                         const int j0 = (col & 63) >> 1;
;                         const f32x4* cs = (const f32x4*)(rope + ((size_t)pos * 32 + j0) * 2);
;                         const f32x4 a = cs[0], b = cs[1];
;                         f32x4 w0, w1;
;                         w0[0] = v0[0] * a[0] - v0[1] * a[1]; w0[1] = v0[1] * a[0] + v0[0] * a[1];
;                         w0[2] = v0[2] * a[2] - v0[3] * a[3]; w0[3] = v0[3] * a[2] + v0[2] * a[3];
;                         w1[0] = v1[0] * b[0] - v1[1] * b[1]; w1[1] = v1[1] * b[0] + v1[0] * b[1];
;                         w1[2] = v1[2] * b[2] - v1[3] * b[3]; w1[3] = v1[3] * b[2] + v1[2] * b[3];
;                         v0 = w0; v1 = w1;
;                     } else if (mode == 2) {
; #pragma unroll
;                         for (int i = 0; i < 4; ++i) { v0[i] = v0[i] * __builtin_amdgcn_rcpf(1.f + __builtin_amdgcn_exp2f(-v0[i] * LOG2E)); v1[i] = v1[i] * __builtin_amdgcn_rcpf(1.f + __builtin_amdgcn_exp2f(-v1[i] * LOG2E)); }
.LBB0_289:
	s_nop 0
	s_cmp_gt_i32 s61, 1
	s_mov_b64 s[0:1], -1
	s_waitcnt vmcnt(10)
	v_fmamk_f32 v0, v227, 0x3a800000, v202
	v_mul_f32_e32 v82, 0x4b800000, v0
	v_cmp_gt_f32_e32 vcc, s18, v0
	s_nop 1
	v_cndmask_b32_e32 v0, v0, v82, vcc
	v_rsq_f32_e32 v0, v0
	s_nop 0
	v_mul_f32_e32 v82, 0x45800000, v0
	v_cndmask_b32_e32 v0, v0, v82, vcc
	v_mul_f32_e32 v82, v162, v0
	v_pk_mul_f32 v[80:81], v[80:81], v[82:83] op_sel_hi:[1,0]
	v_pk_mul_f32 v[78:79], v[78:79], v[82:83] op_sel_hi:[1,0]
	v_pk_mul_f32 v[76:77], v[76:77], v[82:83] op_sel_hi:[1,0]
	v_pk_mul_f32 v[74:75], v[74:75], v[82:83] op_sel_hi:[1,0]
	s_cbranch_scc0 .LBB0_291
	v_mul_f32_e32 v0, 0xbfb8aa3b, v78
	v_exp_f32_e32 v0, v0
	v_mul_f32_e32 v83, 0xbfb8aa3b, v74
	v_exp_f32_e32 v83, v83
	v_mul_f32_e32 v84, 0xbfb8aa3b, v79
	v_add_f32_e32 v0, 1.0, v0
	v_exp_f32_e32 v85, v84
	v_rcp_f32_e32 v84, v0
	v_add_f32_e32 v0, 1.0, v83
	v_mul_f32_e32 v83, 0xbfb8aa3b, v80
	v_exp_f32_e32 v83, v83
	v_mul_f32_e32 v86, 0xbfb8aa3b, v76
	v_exp_f32_e32 v87, v86
	v_rcp_f32_e32 v92, v0
	v_add_f32_e32 v83, 1.0, v83
	v_add_f32_e32 v0, 1.0, v85
	v_rcp_f32_e32 v86, v83
	v_add_f32_e32 v83, 1.0, v87
	v_mul_f32_e32 v87, 0xbfb8aa3b, v81
	v_rcp_f32_e32 v85, v0
	v_mul_f32_e32 v0, 0xbfb8aa3b, v75
	v_exp_f32_e32 v87, v87
	v_mul_f32_e32 v88, 0xbfb8aa3b, v77
	v_exp_f32_e32 v0, v0
	v_exp_f32_e32 v88, v88
	v_rcp_f32_e32 v94, v83
	v_add_f32_e32 v83, 1.0, v87
	v_add_f32_e32 v0, 1.0, v0
	v_rcp_f32_e32 v87, v83
	v_add_f32_e32 v83, 1.0, v88
	v_rcp_f32_e32 v95, v83
	v_rcp_f32_e32 v93, v0
	v_pk_mul_f32 v[88:89], v[80:81], v[86:87]
	v_pk_mul_f32 v[90:91], v[78:79], v[84:85]
	v_pk_mul_f32 v[86:87], v[76:77], v[94:95]
	v_pk_mul_f32 v[84:85], v[74:75], v[92:93]
	s_mov_b64 s[0:1], 0

;     __device__ __forceinline__ void operator()(const f32x4 (&acc)[2][2][4][2], const Unit& u, int wr, int wc, int fr, int fq) const {
;     ...
;                 const int row = u.pm * BM + ai * HALF + wr * 64 + m * 16 + fr;
;                 const float rs = rsqrtf(sumsq[row] * (1.0f / DM) + NORM_EPS) * sc;
;                 const int bb = row >> 13, tt = row & 8191; const size_t R = (size_t)bb * LP + 64 + tt; const int pos = 16 + tt;
; #pragma unroll
;                 for (int bj = 0; bj < 2; ++bj) {
;                     const int col = colb + bj * HALF;
;                     f32x4 v0 = acc[ai][bj][m][0] * rs, v1 = acc[ai][bj][m][1] * rs;
;                     if (mode == 1) {
;                         const int j0 = (col & 63) >> 1;
;                         const f32x4* cs = (const f32x4*)(rope + ((size_t)pos * 32 + j0) * 2);
;                         const f32x4 a = cs[0], b = cs[1];
;                         f32x4 w0, w1;
;                         w0[0] = v0[0] * a[0] - v0[1] * a[1]; w0[1] = v0[1] * a[0] + v0[0] * a[1];
;                         w0[2] = v0[2] * a[2] - v0[3] * a[3]; w0[3] = v0[3] * a[2] + v0[2] * a[3];
;                         w1[0] = v1[0] * b[0] - v1[1] * b[1]; w1[1] = v1[1] * b[0] + v1[0] * b[1];
;                         w1[2] = v1[2] * b[2] - v1[3] * b[3]; w1[3] = v1[3] * b[2] + v1[2] * b[3];
;                         v0 = w0; v1 = w1;
;                     } else if (mode == 2) {
; #pragma unroll
;                         for (int i = 0; i < 4; ++i) { v0[i] = v0[i] * __builtin_amdgcn_rcpf(1.f + __builtin_amdgcn_exp2f(-v0[i] * LOG2E)); v1[i] = v1[i] * __builtin_amdgcn_rcpf(1.f + __builtin_amdgcn_exp2f(-v1[i] * LOG2E)); }
.LBB0_305:
	s_addk_i32 s63, 0x80
	v_or_b32_e32 v66, s63, v115
	v_ashrrev_i32_e32 v67, 31, v66
	v_lshl_add_u64 v[68:69], v[66:67], 2, s[54:55]
	s_nop 0
	s_cmp_gt_i32 s61, 1
	s_mov_b64 s[0:1], -1
	s_waitcnt vmcnt(11)
	v_fmamk_f32 v0, v228, 0x3a800000, v202
	v_mul_f32_e32 v67, 0x4b800000, v0
	v_cmp_gt_f32_e32 vcc, s18, v0
	s_nop 1
	v_cndmask_b32_e32 v0, v0, v67, vcc
	v_rsq_f32_e32 v0, v0
	s_nop 0
	v_mul_f32_e32 v67, 0x45800000, v0
	v_cndmask_b32_e32 v0, v0, v67, vcc
	v_mul_f32_e32 v70, v162, v0
	v_pk_mul_f32 v[64:65], v[64:65], v[70:71] op_sel_hi:[1,0]
	v_pk_mul_f32 v[62:63], v[62:63], v[70:71] op_sel_hi:[1,0]
	v_pk_mul_f32 v[60:61], v[60:61], v[70:71] op_sel_hi:[1,0]
	v_pk_mul_f32 v[58:59], v[58:59], v[70:71] op_sel_hi:[1,0]
	s_cbranch_scc0 .LBB0_307
	v_mul_f32_e32 v0, 0xbfb8aa3b, v62
	v_exp_f32_e32 v0, v0
	v_mul_f32_e32 v67, 0xbfb8aa3b, v58
	v_mul_f32_e32 v71, 0xbfb8aa3b, v63
	v_exp_f32_e32 v67, v67
	v_exp_f32_e32 v71, v71
	v_add_f32_e32 v0, 1.0, v0
	v_rcp_f32_e32 v72, v0
	v_add_f32_e32 v0, 1.0, v67
	v_mul_f32_e32 v67, 0xbfb8aa3b, v64
	v_rcp_f32_e32 v80, v0
	v_add_f32_e32 v0, 1.0, v71
	v_exp_f32_e32 v67, v67
	v_mul_f32_e32 v71, 0xbfb8aa3b, v60
	v_exp_f32_e32 v71, v71
	v_rcp_f32_e32 v73, v0
	v_add_f32_e32 v67, 1.0, v67
	v_rcp_f32_e32 v74, v67
	v_add_f32_e32 v67, 1.0, v71
	v_mul_f32_e32 v71, 0xbfb8aa3b, v65
	v_mul_f32_e32 v0, 0xbfb8aa3b, v59
	v_exp_f32_e32 v71, v71
	v_mul_f32_e32 v75, 0xbfb8aa3b, v61
	v_exp_f32_e32 v0, v0
	v_exp_f32_e32 v76, v75
	v_rcp_f32_e32 v82, v67
	v_add_f32_e32 v67, 1.0, v71
	v_add_f32_e32 v0, 1.0, v0
	v_rcp_f32_e32 v75, v67
	v_add_f32_e32 v67, 1.0, v76
	v_rcp_f32_e32 v83, v67
	v_rcp_f32_e32 v81, v0
	v_pk_mul_f32 v[76:77], v[64:65], v[74:75]
	v_pk_mul_f32 v[78:79], v[62:63], v[72:73]
	v_pk_mul_f32 v[74:75], v[60:61], v[82:83]
	v_pk_mul_f32 v[72:73], v[58:59], v[80:81]
	s_mov_b64 s[0:1], 0

;     __device__ __forceinline__ void operator()(const f32x4 (&acc)[2][2][4][2], const Unit& u, int wr, int wc, int fr, int fq) const {
;     ...
;                 const int row = u.pm * BM + ai * HALF + wr * 64 + m * 16 + fr;
;                 const float rs = rsqrtf(sumsq[row] * (1.0f / DM) + NORM_EPS) * sc;
;                 const int bb = row >> 13, tt = row & 8191; const size_t R = (size_t)bb * LP + 64 + tt; const int pos = 16 + tt;
; #pragma unroll
;                 for (int bj = 0; bj < 2; ++bj) {
;                     const int col = colb + bj * HALF;
;                     f32x4 v0 = acc[ai][bj][m][0] * rs, v1 = acc[ai][bj][m][1] * rs;
;                     if (mode == 1) {
;                         const int j0 = (col & 63) >> 1;
;                         const f32x4* cs = (const f32x4*)(rope + ((size_t)pos * 32 + j0) * 2);
;                         const f32x4 a = cs[0], b = cs[1];
;                         f32x4 w0, w1;
;                         w0[0] = v0[0] * a[0] - v0[1] * a[1]; w0[1] = v0[1] * a[0] + v0[0] * a[1];
;                         w0[2] = v0[2] * a[2] - v0[3] * a[3]; w0[3] = v0[3] * a[2] + v0[2] * a[3];
;                         w1[0] = v1[0] * b[0] - v1[1] * b[1]; w1[1] = v1[1] * b[0] + v1[0] * b[1];
;                         w1[2] = v1[2] * b[2] - v1[3] * b[3]; w1[3] = v1[3] * b[2] + v1[2] * b[3];
;                         v0 = w0; v1 = w1;
;                     } else if (mode == 2) {
; #pragma unroll
;                         for (int i = 0; i < 4; ++i) { v0[i] = v0[i] * __builtin_amdgcn_rcpf(1.f + __builtin_amdgcn_exp2f(-v0[i] * LOG2E)); v1[i] = v1[i] * __builtin_amdgcn_rcpf(1.f + __builtin_amdgcn_exp2f(-v1[i] * LOG2E)); }
.LBB0_321:
	s_nop 0
	s_cmp_gt_i32 s61, 1
	s_mov_b64 s[0:1], -1
	s_waitcnt vmcnt(12)
	v_fmamk_f32 v0, v229, 0x3a800000, v202
	v_mul_f32_e32 v50, 0x4b800000, v0
	v_cmp_gt_f32_e32 vcc, s18, v0
	s_nop 1
	v_cndmask_b32_e32 v0, v0, v50, vcc
	v_rsq_f32_e32 v0, v0
	s_nop 0
	v_mul_f32_e32 v50, 0x45800000, v0
	v_cndmask_b32_e32 v0, v0, v50, vcc
	v_mul_f32_e32 v50, v162, v0
	v_pk_mul_f32 v[48:49], v[48:49], v[50:51] op_sel_hi:[1,0]
	v_pk_mul_f32 v[46:47], v[46:47], v[50:51] op_sel_hi:[1,0]
	v_pk_mul_f32 v[44:45], v[44:45], v[50:51] op_sel_hi:[1,0]
	v_pk_mul_f32 v[42:43], v[42:43], v[50:51] op_sel_hi:[1,0]
	s_cbranch_scc0 .LBB0_323
	v_mul_f32_e32 v0, 0xbfb8aa3b, v46
	v_exp_f32_e32 v0, v0
	v_mul_f32_e32 v51, 0xbfb8aa3b, v42
	v_exp_f32_e32 v51, v51
	v_mul_f32_e32 v52, 0xbfb8aa3b, v47
	v_add_f32_e32 v0, 1.0, v0
	v_exp_f32_e32 v53, v52
	v_rcp_f32_e32 v52, v0
	v_add_f32_e32 v0, 1.0, v51
	v_mul_f32_e32 v51, 0xbfb8aa3b, v48
	v_exp_f32_e32 v51, v51
	v_mul_f32_e32 v54, 0xbfb8aa3b, v44
	v_exp_f32_e32 v55, v54
	v_rcp_f32_e32 v60, v0
	v_add_f32_e32 v51, 1.0, v51
	v_add_f32_e32 v0, 1.0, v53
	v_rcp_f32_e32 v54, v51
	v_add_f32_e32 v51, 1.0, v55
	v_mul_f32_e32 v55, 0xbfb8aa3b, v49
	v_rcp_f32_e32 v53, v0
	v_mul_f32_e32 v0, 0xbfb8aa3b, v43
	v_exp_f32_e32 v55, v55
	v_mul_f32_e32 v56, 0xbfb8aa3b, v45
	v_exp_f32_e32 v0, v0
	v_exp_f32_e32 v56, v56
	v_rcp_f32_e32 v62, v51
	v_add_f32_e32 v51, 1.0, v55
	v_add_f32_e32 v0, 1.0, v0
	v_rcp_f32_e32 v55, v51
	v_add_f32_e32 v51, 1.0, v56
	v_rcp_f32_e32 v63, v51
	v_rcp_f32_e32 v61, v0
	v_pk_mul_f32 v[56:57], v[48:49], v[54:55]
	v_pk_mul_f32 v[58:59], v[46:47], v[52:53]
	v_pk_mul_f32 v[54:55], v[44:45], v[62:63]
	v_pk_mul_f32 v[52:53], v[42:43], v[60:61]
	s_mov_b64 s[0:1], 0

;     __device__ __forceinline__ void operator()(const f32x4 (&acc)[2][2][4][2], const Unit& u, int wr, int wc, int fr, int fq) const {
;     ...
;                 const int row = u.pm * BM + ai * HALF + wr * 64 + m * 16 + fr;
;                 const float rs = rsqrtf(sumsq[row] * (1.0f / DM) + NORM_EPS) * sc;
;                 const int bb = row >> 13, tt = row & 8191; const size_t R = (size_t)bb * LP + 64 + tt; const int pos = 16 + tt;
; #pragma unroll
;                 for (int bj = 0; bj < 2; ++bj) {
;                     const int col = colb + bj * HALF;
;                     f32x4 v0 = acc[ai][bj][m][0] * rs, v1 = acc[ai][bj][m][1] * rs;
;                     if (mode == 1) {
;                         const int j0 = (col & 63) >> 1;
;                         const f32x4* cs = (const f32x4*)(rope + ((size_t)pos * 32 + j0) * 2);
;                         const f32x4 a = cs[0], b = cs[1];
;                         f32x4 w0, w1;
;                         w0[0] = v0[0] * a[0] - v0[1] * a[1]; w0[1] = v0[1] * a[0] + v0[0] * a[1];
;                         w0[2] = v0[2] * a[2] - v0[3] * a[3]; w0[3] = v0[3] * a[2] + v0[2] * a[3];
;                         w1[0] = v1[0] * b[0] - v1[1] * b[1]; w1[1] = v1[1] * b[0] + v1[0] * b[1];
;                         w1[2] = v1[2] * b[2] - v1[3] * b[3]; w1[3] = v1[3] * b[2] + v1[2] * b[3];
;                         v0 = w0; v1 = w1;
;                     } else if (mode == 2) {
; #pragma unroll
;                         for (int i = 0; i < 4; ++i) { v0[i] = v0[i] * __builtin_amdgcn_rcpf(1.f + __builtin_amdgcn_exp2f(-v0[i] * LOG2E)); v1[i] = v1[i] * __builtin_amdgcn_rcpf(1.f + __builtin_amdgcn_exp2f(-v1[i] * LOG2E)); }
.LBB0_337:
	s_nop 0
	s_cmp_gt_i32 s61, 1
	s_mov_b64 s[0:1], -1
	s_waitcnt vmcnt(13)
	v_fmamk_f32 v0, v230, 0x3a800000, v202
	v_mul_f32_e32 v34, 0x4b800000, v0
	v_cmp_gt_f32_e32 vcc, s18, v0
	s_nop 1
	v_cndmask_b32_e32 v0, v0, v34, vcc
	v_rsq_f32_e32 v0, v0
	s_nop 0
	v_mul_f32_e32 v34, 0x45800000, v0
	v_cndmask_b32_e32 v0, v0, v34, vcc
	v_mul_f32_e32 v34, v162, v0
	v_pk_mul_f32 v[32:33], v[32:33], v[34:35] op_sel_hi:[1,0]
	v_pk_mul_f32 v[30:31], v[30:31], v[34:35] op_sel_hi:[1,0]
	v_pk_mul_f32 v[28:29], v[28:29], v[34:35] op_sel_hi:[1,0]
	v_pk_mul_f32 v[26:27], v[26:27], v[34:35] op_sel_hi:[1,0]
	s_cbranch_scc0 .LBB0_339
	v_mul_f32_e32 v0, 0xbfb8aa3b, v30
	v_exp_f32_e32 v0, v0
	v_mul_f32_e32 v35, 0xbfb8aa3b, v26
	v_exp_f32_e32 v35, v35
	v_mul_f32_e32 v36, 0xbfb8aa3b, v31
	v_add_f32_e32 v0, 1.0, v0
	v_exp_f32_e32 v37, v36
	v_rcp_f32_e32 v36, v0
	v_add_f32_e32 v0, 1.0, v35
	v_mul_f32_e32 v35, 0xbfb8aa3b, v32
	v_exp_f32_e32 v35, v35
	v_mul_f32_e32 v38, 0xbfb8aa3b, v28
	v_exp_f32_e32 v39, v38
	v_rcp_f32_e32 v44, v0
	v_add_f32_e32 v35, 1.0, v35
	v_add_f32_e32 v0, 1.0, v37
	v_rcp_f32_e32 v38, v35
	v_add_f32_e32 v35, 1.0, v39
	v_mul_f32_e32 v39, 0xbfb8aa3b, v33
	v_rcp_f32_e32 v37, v0
	v_mul_f32_e32 v0, 0xbfb8aa3b, v27
	v_exp_f32_e32 v39, v39
	v_mul_f32_e32 v40, 0xbfb8aa3b, v29
	v_exp_f32_e32 v0, v0
	v_exp_f32_e32 v40, v40
	v_rcp_f32_e32 v46, v35
	v_add_f32_e32 v35, 1.0, v39
	v_add_f32_e32 v0, 1.0, v0
	v_rcp_f32_e32 v39, v35
	v_add_f32_e32 v35, 1.0, v40
	v_rcp_f32_e32 v47, v35
	v_rcp_f32_e32 v45, v0
	v_pk_mul_f32 v[40:41], v[32:33], v[38:39]
	v_pk_mul_f32 v[42:43], v[30:31], v[36:37]
	v_pk_mul_f32 v[38:39], v[28:29], v[46:47]
	v_pk_mul_f32 v[36:37], v[26:27], v[44:45]
	s_mov_b64 s[0:1], 0

;     __device__ __forceinline__ void operator()(const f32x4 (&acc)[2][2][4][2], const Unit& u, int wr, int wc, int fr, int fq) const {
;     ...
;                 const int row = u.pm * BM + ai * HALF + wr * 64 + m * 16 + fr;
;                 const float rs = rsqrtf(sumsq[row] * (1.0f / DM) + NORM_EPS) * sc;
;                 const int bb = row >> 13, tt = row & 8191; const size_t R = (size_t)bb * LP + 64 + tt; const int pos = 16 + tt;
; #pragma unroll
;                 for (int bj = 0; bj < 2; ++bj) {
;                     const int col = colb + bj * HALF;
;                     f32x4 v0 = acc[ai][bj][m][0] * rs, v1 = acc[ai][bj][m][1] * rs;
;                     if (mode == 1) {
;                         const int j0 = (col & 63) >> 1;
;                         const f32x4* cs = (const f32x4*)(rope + ((size_t)pos * 32 + j0) * 2);
;                         const f32x4 a = cs[0], b = cs[1];
;                         f32x4 w0, w1;
;                         w0[0] = v0[0] * a[0] - v0[1] * a[1]; w0[1] = v0[1] * a[0] + v0[0] * a[1];
;                         w0[2] = v0[2] * a[2] - v0[3] * a[3]; w0[3] = v0[3] * a[2] + v0[2] * a[3];
;                         w1[0] = v1[0] * b[0] - v1[1] * b[1]; w1[1] = v1[1] * b[0] + v1[0] * b[1];
;                         w1[2] = v1[2] * b[2] - v1[3] * b[3]; w1[3] = v1[3] * b[2] + v1[2] * b[3];
;                         v0 = w0; v1 = w1;
;                     } else if (mode == 2) {
; #pragma unroll
;                         for (int i = 0; i < 4; ++i) { v0[i] = v0[i] * __builtin_amdgcn_rcpf(1.f + __builtin_amdgcn_exp2f(-v0[i] * LOG2E)); v1[i] = v1[i] * __builtin_amdgcn_rcpf(1.f + __builtin_amdgcn_exp2f(-v1[i] * LOG2E)); }
.LBB0_353:
	s_nop 0
	s_cmp_gt_i32 s61, 1
	s_mov_b64 s[0:1], -1
	s_waitcnt vmcnt(14)
	v_fmamk_f32 v0, v231, 0x3a800000, v202
	v_mul_f32_e32 v18, 0x4b800000, v0
	v_cmp_gt_f32_e32 vcc, s18, v0
	s_nop 1
	v_cndmask_b32_e32 v0, v0, v18, vcc
	v_rsq_f32_e32 v0, v0
	s_nop 0
	v_mul_f32_e32 v18, 0x45800000, v0
	v_cndmask_b32_e32 v0, v0, v18, vcc
	v_mul_f32_e32 v18, v162, v0
	v_pk_mul_f32 v[16:17], v[16:17], v[18:19] op_sel_hi:[1,0]
	v_pk_mul_f32 v[14:15], v[14:15], v[18:19] op_sel_hi:[1,0]
	v_pk_mul_f32 v[12:13], v[12:13], v[18:19] op_sel_hi:[1,0]
	v_pk_mul_f32 v[10:11], v[10:11], v[18:19] op_sel_hi:[1,0]
	s_cbranch_scc0 .LBB0_355
	v_mul_f32_e32 v0, 0xbfb8aa3b, v14
	v_exp_f32_e32 v0, v0
	v_mul_f32_e32 v19, 0xbfb8aa3b, v10
	v_exp_f32_e32 v19, v19
	v_mul_f32_e32 v20, 0xbfb8aa3b, v15
	v_add_f32_e32 v0, 1.0, v0
	v_exp_f32_e32 v21, v20
	v_rcp_f32_e32 v20, v0
	v_add_f32_e32 v0, 1.0, v19
	v_mul_f32_e32 v19, 0xbfb8aa3b, v16
	v_exp_f32_e32 v19, v19
	v_mul_f32_e32 v22, 0xbfb8aa3b, v12
	v_exp_f32_e32 v23, v22
	v_rcp_f32_e32 v28, v0
	v_add_f32_e32 v19, 1.0, v19
	v_add_f32_e32 v0, 1.0, v21
	v_rcp_f32_e32 v22, v19
	v_add_f32_e32 v19, 1.0, v23
	v_mul_f32_e32 v23, 0xbfb8aa3b, v17
	v_rcp_f32_e32 v21, v0
	v_mul_f32_e32 v0, 0xbfb8aa3b, v11
	v_exp_f32_e32 v23, v23
	v_mul_f32_e32 v24, 0xbfb8aa3b, v13
	v_exp_f32_e32 v0, v0
	v_exp_f32_e32 v24, v24
	v_rcp_f32_e32 v30, v19
	v_add_f32_e32 v19, 1.0, v23
	v_add_f32_e32 v0, 1.0, v0
	v_rcp_f32_e32 v23, v19
	v_add_f32_e32 v19, 1.0, v24
	v_rcp_f32_e32 v31, v19
	v_rcp_f32_e32 v29, v0
	v_pk_mul_f32 v[24:25], v[16:17], v[22:23]
	v_pk_mul_f32 v[26:27], v[14:15], v[20:21]
	v_pk_mul_f32 v[22:23], v[12:13], v[30:31]
	v_pk_mul_f32 v[20:21], v[10:11], v[28:29]
	s_mov_b64 s[0:1], 0
